# plus dsa_prep: 4 q-head loads per row issued together with counted vmcnt (was load-wait-store ladder)
# speedup vs baseline: 1.0026x; 1.0026x over previous
; __device__ __forceinline__ unsigned pk2(float lo, float hi) { const f32x2 v = {lo, hi}; const hwbf16x2 b = __builtin_convertvector(v, hwbf16x2); return __builtin_bit_cast(unsigned, b); }
; __device__ __forceinline__ void dsa_prep(const Args& a, unsigned char* lds, int tid) {
;     ...
;         for (int i = 0; i < 8; ++i) {
;             const int row = t0 + 8 * w + i;
;             const bf16* src = QKVI + (size_t)row * QKVI_LD;
; #pragma unroll
;             for (int j = 0; j < 5; ++j) {
;                 const int hh = j * 4 + grp, col = hh * 64 + 4 * sub;
;                 const u32x2 x = *(const u32x2*)(src + col);
;                 f32x4 v = (f32x4){bflo(x.x), bfhi(x.x), bflo(x.y), bfhi(x.y)};
;                 float ss = (v.x * v.x + v.y * v.y) + (v.z * v.z + v.w * v.w);
;                 ss = row16_sum(ss);
;                 const float rstd = __builtin_amdgcn_rsqf(ss * (1.f / 64.f) + 1e-6f);
;                 if (j < 4) { v = v * rstd * qn * QSCALE; u32x2 o; o.x = pk2(v.x, v.y); o.y = pk2(v.z, v.w); *(u32x2*)(QN + (size_t)row * D + col) = o; }
;                 else { v = v * rstd * kn; u32x2 o; o.x = pk2(v.x, v.y); o.y = pk2(v.z, v.w); *(u32x2*)(KN + (size_t)row * 256 + (col - 1024)) = o; }
.LBB0_575:
	v_lshl_add_u64 v[58:59], s[16:17], 0, v[52:53]
	v_add_co_u32_e32 v58, vcc, 0x9d00000, v58
	v_lshl_add_u64 v[62:63], s[16:17], 0, v[50:51]
	s_nop 0
	v_addc_co_u32_e32 v59, vcc, 0, v59, vcc
	global_load_dwordx2 v[100:101], v[58:59], off
	global_load_dwordx2 v[102:103], v[58:59], off offset:512
	global_load_dwordx2 v[104:105], v[58:59], off offset:1024
	global_load_dwordx2 v[60:61], v[58:59], off offset:1536
	s_mov_b32 s12, 0x12d00000
	v_add_co_u32_e32 v62, vcc, s12, v62
	s_waitcnt vmcnt(3)
	v_lshlrev_b32_e32 v65, 16, v101
	v_lshlrev_b32_e32 v64, 16, v100
	v_and_b32_e32 v101, 0xffff0000, v101
	v_and_b32_e32 v100, 0xffff0000, v100
	v_pk_mul_f32 v[66:67], v[100:101], v[100:101]
	v_mov_b32_e32 v72, v65
	v_pk_fma_f32 v[66:67], v[64:65], v[64:65], v[66:67]
	v_mov_b32_e32 v73, v101
	v_add_f32_e32 v29, v66, v67
	v_mov_b32_e32 v65, v100
	v_addc_co_u32_e32 v63, vcc, 0, v63, vcc
	v_add_f32_dpp v29, v29, v29 quad_perm:[1,0,3,2] row_mask:0xf bank_mask:0xf bound_ctrl:1
	s_nop 1
	v_add_f32_dpp v29, v29, v29 quad_perm:[2,3,0,1] row_mask:0xf bank_mask:0xf bound_ctrl:1
	s_nop 1
	v_add_f32_dpp v29, v29, v29 row_half_mirror row_mask:0xf bank_mask:0xf bound_ctrl:1
	s_nop 1
	v_add_f32_dpp v29, v29, v29 row_mirror row_mask:0xf bank_mask:0xf bound_ctrl:1
	v_fmamk_f32 v29, v29, 0x3c800000, v23
	v_rsq_f32_e32 v66, v29
	s_nop 0
	v_pk_mul_f32 v[100:101], v[66:67], v[72:73] op_sel_hi:[0,1]
	v_pk_mul_f32 v[64:65], v[66:67], v[64:65] op_sel_hi:[0,1]
	v_pk_mul_f32 v[64:65], v[0:1], v[64:65]
	v_pk_mul_f32 v[100:101], v[2:3], v[100:101]
	v_pk_mul_f32 v[64:65], v[64:65], s[8:9] op_sel_hi:[1,0]
	v_pk_mul_f32 v[100:101], v[100:101], s[8:9] op_sel_hi:[1,0]
	v_cvt_pk_bf16_f32 v64, v64, v65
	v_cvt_pk_bf16_f32 v65, v100, v101
	global_store_dwordx2 v[62:63], v[64:65], off
	s_waitcnt vmcnt(3)
	v_lshlrev_b32_e32 v65, 16, v103
	v_lshlrev_b32_e32 v64, 16, v102
	v_and_b32_e32 v103, 0xffff0000, v103
	v_and_b32_e32 v102, 0xffff0000, v102
	v_pk_mul_f32 v[66:67], v[102:103], v[102:103]
	v_mov_b32_e32 v72, v65
	v_pk_fma_f32 v[66:67], v[64:65], v[64:65], v[66:67]
	v_mov_b32_e32 v73, v103
	v_add_f32_e32 v29, v66, v67
	v_mov_b32_e32 v65, v102
	s_nop 0
	v_add_f32_dpp v29, v29, v29 quad_perm:[1,0,3,2] row_mask:0xf bank_mask:0xf bound_ctrl:1
	s_nop 1
	v_add_f32_dpp v29, v29, v29 quad_perm:[2,3,0,1] row_mask:0xf bank_mask:0xf bound_ctrl:1
	s_nop 1
	v_add_f32_dpp v29, v29, v29 row_half_mirror row_mask:0xf bank_mask:0xf bound_ctrl:1
	s_nop 1
	v_add_f32_dpp v29, v29, v29 row_mirror row_mask:0xf bank_mask:0xf bound_ctrl:1
	v_fmamk_f32 v29, v29, 0x3c800000, v23
	v_rsq_f32_e32 v66, v29
	s_nop 0
	v_pk_mul_f32 v[102:103], v[66:67], v[72:73] op_sel_hi:[0,1]
	v_pk_mul_f32 v[64:65], v[66:67], v[64:65] op_sel_hi:[0,1]
	v_pk_mul_f32 v[64:65], v[0:1], v[64:65]
	v_pk_mul_f32 v[102:103], v[2:3], v[102:103]
	v_pk_mul_f32 v[64:65], v[64:65], s[8:9] op_sel_hi:[1,0]
	v_pk_mul_f32 v[102:103], v[102:103], s[8:9] op_sel_hi:[1,0]
	v_cvt_pk_bf16_f32 v64, v64, v65
	v_cvt_pk_bf16_f32 v65, v102, v103
	global_store_dwordx2 v[62:63], v[64:65], off offset:512
	s_waitcnt vmcnt(3)
	v_lshlrev_b32_e32 v65, 16, v105
	v_lshlrev_b32_e32 v64, 16, v104
	v_and_b32_e32 v105, 0xffff0000, v105
	v_and_b32_e32 v104, 0xffff0000, v104
	v_pk_mul_f32 v[66:67], v[104:105], v[104:105]
	v_mov_b32_e32 v72, v65
	v_pk_fma_f32 v[66:67], v[64:65], v[64:65], v[66:67]
	v_mov_b32_e32 v73, v105
	v_add_f32_e32 v29, v66, v67
	v_mov_b32_e32 v65, v104
	s_nop 0
	v_add_f32_dpp v29, v29, v29 quad_perm:[1,0,3,2] row_mask:0xf bank_mask:0xf bound_ctrl:1
	s_nop 1
	v_add_f32_dpp v29, v29, v29 quad_perm:[2,3,0,1] row_mask:0xf bank_mask:0xf bound_ctrl:1
	s_nop 1
	v_add_f32_dpp v29, v29, v29 row_half_mirror row_mask:0xf bank_mask:0xf bound_ctrl:1
	s_nop 1
	v_add_f32_dpp v29, v29, v29 row_mirror row_mask:0xf bank_mask:0xf bound_ctrl:1
	v_fmamk_f32 v29, v29, 0x3c800000, v23
	v_rsq_f32_e32 v66, v29
	s_nop 0
	v_pk_mul_f32 v[104:105], v[66:67], v[72:73] op_sel_hi:[0,1]
	v_pk_mul_f32 v[64:65], v[66:67], v[64:65] op_sel_hi:[0,1]
	v_pk_mul_f32 v[64:65], v[0:1], v[64:65]
	v_pk_mul_f32 v[104:105], v[2:3], v[104:105]
	v_pk_mul_f32 v[64:65], v[64:65], s[8:9] op_sel_hi:[1,0]
	v_pk_mul_f32 v[104:105], v[104:105], s[8:9] op_sel_hi:[1,0]
	v_cvt_pk_bf16_f32 v64, v64, v65
	v_cvt_pk_bf16_f32 v65, v104, v105
	global_store_dwordx2 v[62:63], v[64:65], off offset:1024
	s_waitcnt vmcnt(3)
; __device__ __forceinline__ unsigned pk2(float lo, float hi) { const f32x2 v = {lo, hi}; const hwbf16x2 b = __builtin_convertvector(v, hwbf16x2); return __builtin_bit_cast(unsigned, b); }
; __device__ __forceinline__ void dsa_prep(const Args& a, unsigned char* lds, int tid) {
;     ...
;             for (int j = 0; j < 5; ++j) {
;                 const int hh = j * 4 + grp, col = hh * 64 + 4 * sub;
;                 const u32x2 x = *(const u32x2*)(src + col);
;                 f32x4 v = (f32x4){bflo(x.x), bfhi(x.x), bflo(x.y), bfhi(x.y)};
;                 float ss = (v.x * v.x + v.y * v.y) + (v.z * v.z + v.w * v.w);
;                 ss = row16_sum(ss);
;                 const float rstd = __builtin_amdgcn_rsqf(ss * (1.f / 64.f) + 1e-6f);
;                 if (j < 4) { v = v * rstd * qn * QSCALE; u32x2 o; o.x = pk2(v.x, v.y); o.y = pk2(v.z, v.w); *(u32x2*)(QN + (size_t)row * D + col) = o; }
;                 else { v = v * rstd * kn; u32x2 o; o.x = pk2(v.x, v.y); o.y = pk2(v.z, v.w); *(u32x2*)(KN + (size_t)row * 256 + (col - 1024)) = o; }
;             }
;             {
;                 const u32x2 x = *(const u32x2*)(src + 2048 + 4 * sub);
;                 f32x4 v = (f32x4){bflo(x.x), bfhi(x.x), bflo(x.y), bfhi(x.y)};
;                 float ss = (v.x * v.x + v.y * v.y) + (v.z * v.z + v.w * v.w);
;                 ss = row16_sum(ss);
;                 const float rstd = __builtin_amdgcn_rsqf(ss * (1.f / 64.f) + 1e-6f);
;                 v = v * rstd * ikn;
;                 if (grp == 0) { u32x2 o; o.x = pk2(v.x, v.y); o.y = pk2(v.z, v.w); *(u32x2*)(IKN + (size_t)row * 64 + 4 * sub) = o; }
	v_lshlrev_b32_e32 v65, 16, v61
	v_lshlrev_b32_e32 v64, 16, v60
	v_and_b32_e32 v61, 0xffff0000, v61
	v_and_b32_e32 v60, 0xffff0000, v60
	v_pk_mul_f32 v[66:67], v[60:61], v[60:61]
	v_mov_b32_e32 v72, v65
	v_pk_fma_f32 v[66:67], v[64:65], v[64:65], v[66:67]
	v_mov_b32_e32 v73, v61
	v_add_f32_e32 v29, v66, v67
	v_mov_b32_e32 v65, v60
	s_nop 0
	v_add_f32_dpp v29, v29, v29 quad_perm:[1,0,3,2] row_mask:0xf bank_mask:0xf bound_ctrl:1
	s_nop 1
	v_add_f32_dpp v29, v29, v29 quad_perm:[2,3,0,1] row_mask:0xf bank_mask:0xf bound_ctrl:1
	s_nop 1
	v_add_f32_dpp v29, v29, v29 row_half_mirror row_mask:0xf bank_mask:0xf bound_ctrl:1
	s_nop 1
	v_add_f32_dpp v29, v29, v29 row_mirror row_mask:0xf bank_mask:0xf bound_ctrl:1
	v_fmamk_f32 v29, v29, 0x3c800000, v23
	v_rsq_f32_e32 v66, v29
	s_nop 0
	v_pk_mul_f32 v[60:61], v[66:67], v[72:73] op_sel_hi:[0,1]
	v_pk_mul_f32 v[64:65], v[66:67], v[64:65] op_sel_hi:[0,1]
	v_pk_mul_f32 v[64:65], v[0:1], v[64:65]
	v_pk_mul_f32 v[60:61], v[2:3], v[60:61]
	v_pk_mul_f32 v[64:65], v[64:65], s[8:9] op_sel_hi:[1,0]
	v_pk_mul_f32 v[60:61], v[60:61], s[8:9] op_sel_hi:[1,0]
	v_cvt_pk_bf16_f32 v64, v64, v65
	v_cvt_pk_bf16_f32 v65, v60, v61
	global_store_dwordx2 v[62:63], v[64:65], off offset:1536
	global_load_dwordx2 v[58:59], v[58:59], off offset:2048
	v_lshl_add_u64 v[60:61], s[16:17], 0, v[48:49]
	v_lshl_add_u64 v[62:63], s[16:17], 0, v[54:55]
	s_waitcnt vmcnt(0)
	v_lshlrev_b32_e32 v65, 16, v59
	v_lshlrev_b32_e32 v64, 16, v58
	v_and_b32_e32 v59, 0xffff0000, v59
	v_and_b32_e32 v58, 0xffff0000, v58
	v_pk_mul_f32 v[66:67], v[58:59], v[58:59]
	v_mov_b32_e32 v72, v64
	v_pk_fma_f32 v[66:67], v[64:65], v[64:65], v[66:67]
	v_mov_b32_e32 v73, v58
	v_add_f32_e32 v29, v66, v67
	v_mov_b32_e32 v58, v65
	s_nop 0
	v_add_f32_dpp v29, v29, v29 quad_perm:[1,0,3,2] row_mask:0xf bank_mask:0xf bound_ctrl:1
	s_nop 1
	v_add_f32_dpp v29, v29, v29 quad_perm:[2,3,0,1] row_mask:0xf bank_mask:0xf bound_ctrl:1
	s_nop 1
	v_add_f32_dpp v29, v29, v29 row_half_mirror row_mask:0xf bank_mask:0xf bound_ctrl:1
	s_nop 1
	v_add_f32_dpp v29, v29, v29 row_mirror row_mask:0xf bank_mask:0xf bound_ctrl:1
	v_fmamk_f32 v29, v29, 0x3c800000, v23
	v_rsq_f32_e32 v66, v29
	s_nop 0
	v_pk_mul_f32 v[64:65], v[66:67], v[72:73] op_sel_hi:[0,1]
	v_pk_mul_f32 v[58:59], v[66:67], v[58:59] op_sel_hi:[0,1]
	v_pk_mul_f32 v[58:59], v[6:7], v[58:59]
	v_pk_mul_f32 v[64:65], v[4:5], v[64:65]
	s_nop 0
	v_cvt_pk_bf16_f32 v64, v64, v65
	v_cvt_pk_bf16_f32 v65, v58, v59
	global_store_dwordx2 v[60:61], v[64:65], off
	global_load_dwordx2 v[58:59], v[62:63], off
	s_waitcnt vmcnt(0)
	v_lshlrev_b32_e32 v60, 16, v58
	v_and_b32_e32 v61, 0xffff0000, v58
	v_lshlrev_b32_e32 v58, 16, v59
	v_and_b32_e32 v59, 0xffff0000, v59
	v_mul_f32_e32 v29, v61, v61
	v_mul_f32_e32 v41, v59, v59
	v_fmac_f32_e32 v29, v60, v60
	v_fmac_f32_e32 v41, v58, v58
	v_add_f32_e32 v29, v29, v41
	s_nop 1
	v_add_f32_dpp v29, v29, v29 quad_perm:[1,0,3,2] row_mask:0xf bank_mask:0xf bound_ctrl:1
	s_nop 1
	v_add_f32_dpp v29, v29, v29 quad_perm:[2,3,0,1] row_mask:0xf bank_mask:0xf bound_ctrl:1
	s_nop 1
	v_add_f32_dpp v29, v29, v29 row_half_mirror row_mask:0xf bank_mask:0xf bound_ctrl:1
	s_nop 1
	v_mov_b32_dpp v41, v29 row_mirror row_mask:0xf bank_mask:0xf bound_ctrl:1
	s_and_saveexec_b64 s[12:13], s[0:1]
	s_cbranch_execz .LBB0_577
	v_add_f32_e32 v29, v29, v41
	v_fmamk_f32 v29, v29, 0x3c800000, v23
	v_rsq_f32_e32 v62, v29
	s_nop 0
	v_pk_mul_f32 v[60:61], v[60:61], v[62:63] op_sel_hi:[1,0]
	v_pk_mul_f32 v[58:59], v[58:59], v[62:63] op_sel_hi:[1,0]
	v_pk_mul_f32 v[60:61], v[8:9], v[60:61]
	v_pk_mul_f32 v[58:59], v[10:11], v[58:59]
	v_cvt_pk_bf16_f32 v60, v60, v61
	v_cvt_pk_bf16_f32 v61, v58, v59
	v_lshl_add_u64 v[58:59], s[16:17], 0, v[44:45]
	global_store_dwordx2 v[58:59], v[60:61], off

; __device__ __forceinline__ unsigned pk2(float lo, float hi) { const f32x2 v = {lo, hi}; const hwbf16x2 b = __builtin_convertvector(v, hwbf16x2); return __builtin_bit_cast(unsigned, b); }
; __device__ __forceinline__ void dsa_prep(const Args& a, unsigned char* lds, int tid) {
;     ...
;         for (int i = 0; i < 8; ++i) {
;             const int row = t0 + 8 * w + i;
;             const bf16* src = QKVI + (size_t)row * QKVI_LD;
; #pragma unroll
;             for (int j = 0; j < 5; ++j) {
;                 const int hh = j * 4 + grp, col = hh * 64 + 4 * sub;
;                 const u32x2 x = *(const u32x2*)(src + col);
;                 f32x4 v = (f32x4){bflo(x.x), bfhi(x.x), bflo(x.y), bfhi(x.y)};
;                 float ss = (v.x * v.x + v.y * v.y) + (v.z * v.z + v.w * v.w);
;                 ss = row16_sum(ss);
;                 const float rstd = __builtin_amdgcn_rsqf(ss * (1.f / 64.f) + 1e-6f);
;                 if (j < 4) { v = v * rstd * qn * QSCALE; u32x2 o; o.x = pk2(v.x, v.y); o.y = pk2(v.z, v.w); *(u32x2*)(QN + (size_t)row * D + col) = o; }
;                 else { v = v * rstd * kn; u32x2 o; o.x = pk2(v.x, v.y); o.y = pk2(v.z, v.w); *(u32x2*)(KN + (size_t)row * 256 + (col - 1024)) = o; }
.LBB0_579:
	s_or_b64 exec, exec, s[12:13]
	v_readlane_b32 s12, v248, 61
	v_add_u32_e32 v29, s6, v28
	v_readlane_b32 s13, v248, 62
	v_add_u32_e32 v60, 1, v29
	v_ashrrev_i32_e32 v61, 31, v60
	v_mov_b64_e32 v[58:59], s[12:13]
	v_mad_i64_i32 v[62:63], s[12:13], v60, s22, v[58:59]
	v_lshl_add_u64 v[58:59], v[62:63], 0, v[12:13]
	global_load_dwordx2 v[100:101], v[58:59], off
	global_load_dwordx2 v[102:103], v[58:59], off offset:512
	global_load_dwordx2 v[104:105], v[58:59], off offset:1024
	global_load_dwordx2 v[64:65], v[58:59], off offset:1536
	v_lshlrev_b64 v[66:67], 11, v[60:61]
	v_lshl_add_u64 v[66:67], v[26:27], 0, v[66:67]
	s_waitcnt vmcnt(3)
	v_lshlrev_b32_e32 v73, 16, v101
	v_lshlrev_b32_e32 v72, 16, v100
	v_and_b32_e32 v101, 0xffff0000, v101
	v_and_b32_e32 v100, 0xffff0000, v100
	v_pk_mul_f32 v[74:75], v[100:101], v[100:101]
	v_mov_b32_e32 v76, v73
	v_pk_fma_f32 v[74:75], v[72:73], v[72:73], v[74:75]
	v_mov_b32_e32 v77, v101
	v_add_f32_e32 v41, v74, v75
	v_mov_b32_e32 v73, v100
	s_nop 0
	v_add_f32_dpp v41, v41, v41 quad_perm:[1,0,3,2] row_mask:0xf bank_mask:0xf bound_ctrl:1
	s_nop 1
	v_add_f32_dpp v41, v41, v41 quad_perm:[2,3,0,1] row_mask:0xf bank_mask:0xf bound_ctrl:1
	s_nop 1
	v_add_f32_dpp v41, v41, v41 row_half_mirror row_mask:0xf bank_mask:0xf bound_ctrl:1
	s_nop 1
	v_add_f32_dpp v41, v41, v41 row_mirror row_mask:0xf bank_mask:0xf bound_ctrl:1
	v_fmamk_f32 v41, v41, 0x3c800000, v23
	v_rsq_f32_e32 v74, v41
	s_nop 0
	v_pk_mul_f32 v[100:101], v[74:75], v[76:77] op_sel_hi:[0,1]
	v_pk_mul_f32 v[72:73], v[74:75], v[72:73] op_sel_hi:[0,1]
	v_pk_mul_f32 v[72:73], v[0:1], v[72:73]
	v_pk_mul_f32 v[100:101], v[2:3], v[100:101]
	v_pk_mul_f32 v[72:73], v[72:73], s[8:9] op_sel_hi:[1,0]
	v_pk_mul_f32 v[100:101], v[100:101], s[8:9] op_sel_hi:[1,0]
	v_cvt_pk_bf16_f32 v72, v72, v73
	v_cvt_pk_bf16_f32 v73, v100, v101
	global_store_dwordx2 v[66:67], v[72:73], off
	s_waitcnt vmcnt(3)
	v_lshlrev_b32_e32 v73, 16, v103
	v_lshlrev_b32_e32 v72, 16, v102
	v_and_b32_e32 v103, 0xffff0000, v103
	v_and_b32_e32 v102, 0xffff0000, v102
	v_pk_mul_f32 v[74:75], v[102:103], v[102:103]
	v_mov_b32_e32 v76, v73
	v_pk_fma_f32 v[74:75], v[72:73], v[72:73], v[74:75]
	v_mov_b32_e32 v77, v103
	v_add_f32_e32 v41, v74, v75
	v_mov_b32_e32 v73, v102
	s_nop 0
	v_add_f32_dpp v41, v41, v41 quad_perm:[1,0,3,2] row_mask:0xf bank_mask:0xf bound_ctrl:1
	s_nop 1
	v_add_f32_dpp v41, v41, v41 quad_perm:[2,3,0,1] row_mask:0xf bank_mask:0xf bound_ctrl:1
	s_nop 1
	v_add_f32_dpp v41, v41, v41 row_half_mirror row_mask:0xf bank_mask:0xf bound_ctrl:1
	s_nop 1
	v_add_f32_dpp v41, v41, v41 row_mirror row_mask:0xf bank_mask:0xf bound_ctrl:1
	v_fmamk_f32 v41, v41, 0x3c800000, v23
	v_rsq_f32_e32 v74, v41
	s_nop 0
	v_pk_mul_f32 v[102:103], v[74:75], v[76:77] op_sel_hi:[0,1]
	v_pk_mul_f32 v[72:73], v[74:75], v[72:73] op_sel_hi:[0,1]
	v_pk_mul_f32 v[72:73], v[0:1], v[72:73]
	v_pk_mul_f32 v[102:103], v[2:3], v[102:103]
	v_pk_mul_f32 v[72:73], v[72:73], s[8:9] op_sel_hi:[1,0]
	v_pk_mul_f32 v[102:103], v[102:103], s[8:9] op_sel_hi:[1,0]
	v_cvt_pk_bf16_f32 v72, v72, v73
	v_cvt_pk_bf16_f32 v73, v102, v103
	global_store_dwordx2 v[66:67], v[72:73], off offset:512
	s_waitcnt vmcnt(3)
	v_lshlrev_b32_e32 v73, 16, v105
	v_lshlrev_b32_e32 v72, 16, v104
	v_and_b32_e32 v105, 0xffff0000, v105
	v_and_b32_e32 v104, 0xffff0000, v104
	v_pk_mul_f32 v[74:75], v[104:105], v[104:105]
	v_mov_b32_e32 v76, v73
	v_pk_fma_f32 v[74:75], v[72:73], v[72:73], v[74:75]
	v_mov_b32_e32 v77, v105
	v_add_f32_e32 v41, v74, v75
	v_mov_b32_e32 v73, v104
	s_nop 0
	v_add_f32_dpp v41, v41, v41 quad_perm:[1,0,3,2] row_mask:0xf bank_mask:0xf bound_ctrl:1
	s_nop 1
	v_add_f32_dpp v41, v41, v41 quad_perm:[2,3,0,1] row_mask:0xf bank_mask:0xf bound_ctrl:1
	s_nop 1
	v_add_f32_dpp v41, v41, v41 row_half_mirror row_mask:0xf bank_mask:0xf bound_ctrl:1
	s_nop 1
	v_add_f32_dpp v41, v41, v41 row_mirror row_mask:0xf bank_mask:0xf bound_ctrl:1
	v_fmamk_f32 v41, v41, 0x3c800000, v23
	v_rsq_f32_e32 v74, v41
	s_nop 0
	v_pk_mul_f32 v[104:105], v[74:75], v[76:77] op_sel_hi:[0,1]
	v_pk_mul_f32 v[72:73], v[74:75], v[72:73] op_sel_hi:[0,1]
	v_pk_mul_f32 v[72:73], v[0:1], v[72:73]
	v_pk_mul_f32 v[104:105], v[2:3], v[104:105]
	v_pk_mul_f32 v[72:73], v[72:73], s[8:9] op_sel_hi:[1,0]
	v_pk_mul_f32 v[104:105], v[104:105], s[8:9] op_sel_hi:[1,0]
	v_cvt_pk_bf16_f32 v72, v72, v73
	v_cvt_pk_bf16_f32 v73, v104, v105
	global_store_dwordx2 v[66:67], v[72:73], off offset:1024
	s_waitcnt vmcnt(3)
; __device__ __forceinline__ unsigned pk2(float lo, float hi) { const f32x2 v = {lo, hi}; const hwbf16x2 b = __builtin_convertvector(v, hwbf16x2); return __builtin_bit_cast(unsigned, b); }
; __device__ __forceinline__ void dsa_prep(const Args& a, unsigned char* lds, int tid) {
;     ...
;             for (int j = 0; j < 5; ++j) {
;                 const int hh = j * 4 + grp, col = hh * 64 + 4 * sub;
;                 const u32x2 x = *(const u32x2*)(src + col);
;                 f32x4 v = (f32x4){bflo(x.x), bfhi(x.x), bflo(x.y), bfhi(x.y)};
;                 float ss = (v.x * v.x + v.y * v.y) + (v.z * v.z + v.w * v.w);
;                 ss = row16_sum(ss);
;                 const float rstd = __builtin_amdgcn_rsqf(ss * (1.f / 64.f) + 1e-6f);
;                 if (j < 4) { v = v * rstd * qn * QSCALE; u32x2 o; o.x = pk2(v.x, v.y); o.y = pk2(v.z, v.w); *(u32x2*)(QN + (size_t)row * D + col) = o; }
;                 else { v = v * rstd * kn; u32x2 o; o.x = pk2(v.x, v.y); o.y = pk2(v.z, v.w); *(u32x2*)(KN + (size_t)row * 256 + (col - 1024)) = o; }
;             }
;             {
;                 const u32x2 x = *(const u32x2*)(src + 2048 + 4 * sub);
;                 f32x4 v = (f32x4){bflo(x.x), bfhi(x.x), bflo(x.y), bfhi(x.y)};
;                 float ss = (v.x * v.x + v.y * v.y) + (v.z * v.z + v.w * v.w);
;                 ss = row16_sum(ss);
;                 const float rstd = __builtin_amdgcn_rsqf(ss * (1.f / 64.f) + 1e-6f);
;                 v = v * rstd * ikn;
;                 if (grp == 0) { u32x2 o; o.x = pk2(v.x, v.y); o.y = pk2(v.z, v.w); *(u32x2*)(IKN + (size_t)row * 64 + 4 * sub) = o; }
	v_lshlrev_b32_e32 v73, 16, v65
	v_lshlrev_b32_e32 v72, 16, v64
	v_and_b32_e32 v65, 0xffff0000, v65
	v_and_b32_e32 v64, 0xffff0000, v64
	v_pk_mul_f32 v[74:75], v[64:65], v[64:65]
	v_mov_b32_e32 v76, v73
	v_pk_fma_f32 v[74:75], v[72:73], v[72:73], v[74:75]
	v_mov_b32_e32 v77, v65
	v_add_f32_e32 v41, v74, v75
	v_mov_b32_e32 v73, v64
	s_nop 0
	v_add_f32_dpp v41, v41, v41 quad_perm:[1,0,3,2] row_mask:0xf bank_mask:0xf bound_ctrl:1
	s_nop 1
	v_add_f32_dpp v41, v41, v41 quad_perm:[2,3,0,1] row_mask:0xf bank_mask:0xf bound_ctrl:1
	s_nop 1
	v_add_f32_dpp v41, v41, v41 row_half_mirror row_mask:0xf bank_mask:0xf bound_ctrl:1
	s_nop 1
	v_add_f32_dpp v41, v41, v41 row_mirror row_mask:0xf bank_mask:0xf bound_ctrl:1
	v_fmamk_f32 v41, v41, 0x3c800000, v23
	v_rsq_f32_e32 v74, v41
	v_mov_b32_e32 v41, v13
	v_pk_mul_f32 v[64:65], v[74:75], v[76:77] op_sel_hi:[0,1]
	v_pk_mul_f32 v[72:73], v[74:75], v[72:73] op_sel_hi:[0,1]
	v_pk_mul_f32 v[72:73], v[0:1], v[72:73]
	v_pk_mul_f32 v[64:65], v[2:3], v[64:65]
	v_pk_mul_f32 v[72:73], v[72:73], s[8:9] op_sel_hi:[1,0]
	v_pk_mul_f32 v[64:65], v[64:65], s[8:9] op_sel_hi:[1,0]
	v_cvt_pk_bf16_f32 v72, v72, v73
	v_cvt_pk_bf16_f32 v73, v64, v65
	global_store_dwordx2 v[66:67], v[72:73], off offset:1536
	global_load_dwordx2 v[58:59], v[58:59], off offset:2048
	v_lshl_add_u64 v[66:67], v[62:63], 0, v[40:41]
	v_lshlrev_b64 v[64:65], 9, v[60:61]
	v_add_co_u32_e32 v66, vcc, s9, v66
	v_lshl_add_u64 v[64:65], v[24:25], 0, v[64:65]
	s_nop 0
	v_addc_co_u32_e32 v67, vcc, 0, v67, vcc
	v_add_co_u32_e32 v64, vcc, s21, v64
	s_waitcnt vmcnt(0)
	v_lshlrev_b32_e32 v73, 16, v59
	v_lshlrev_b32_e32 v72, 16, v58
	v_and_b32_e32 v59, 0xffff0000, v59
	v_and_b32_e32 v58, 0xffff0000, v58
	v_pk_mul_f32 v[74:75], v[58:59], v[58:59]
	v_mov_b32_e32 v76, v72
	v_pk_fma_f32 v[74:75], v[72:73], v[72:73], v[74:75]
	v_mov_b32_e32 v77, v58
	v_add_f32_e32 v41, v74, v75
	v_mov_b32_e32 v58, v73
	v_addc_co_u32_e32 v65, vcc, 0, v65, vcc
	v_add_f32_dpp v41, v41, v41 quad_perm:[1,0,3,2] row_mask:0xf bank_mask:0xf bound_ctrl:1
	s_nop 1
	v_add_f32_dpp v41, v41, v41 quad_perm:[2,3,0,1] row_mask:0xf bank_mask:0xf bound_ctrl:1
	s_nop 1
	v_add_f32_dpp v41, v41, v41 row_half_mirror row_mask:0xf bank_mask:0xf bound_ctrl:1
	s_nop 1
	v_add_f32_dpp v41, v41, v41 row_mirror row_mask:0xf bank_mask:0xf bound_ctrl:1
	v_fmamk_f32 v41, v41, 0x3c800000, v23
	v_rsq_f32_e32 v74, v41
	s_nop 0
	v_pk_mul_f32 v[72:73], v[74:75], v[76:77] op_sel_hi:[0,1]
	v_pk_mul_f32 v[58:59], v[74:75], v[58:59] op_sel_hi:[0,1]
	v_pk_mul_f32 v[58:59], v[6:7], v[58:59]
	v_pk_mul_f32 v[72:73], v[4:5], v[72:73]
	s_nop 0
	v_cvt_pk_bf16_f32 v72, v72, v73
	v_cvt_pk_bf16_f32 v73, v58, v59
	global_store_dwordx2 v[64:65], v[72:73], off
	global_load_dwordx2 v[58:59], v[66:67], off
	s_waitcnt vmcnt(0)
	v_lshlrev_b32_e32 v64, 16, v58
	v_and_b32_e32 v65, 0xffff0000, v58
	v_lshlrev_b32_e32 v58, 16, v59
	v_and_b32_e32 v59, 0xffff0000, v59
	v_mul_f32_e32 v41, v65, v65
	v_mul_f32_e32 v43, v59, v59
	v_fmac_f32_e32 v41, v64, v64
	v_fmac_f32_e32 v43, v58, v58
	v_add_f32_e32 v41, v41, v43
	s_nop 1
	v_add_f32_dpp v41, v41, v41 quad_perm:[1,0,3,2] row_mask:0xf bank_mask:0xf bound_ctrl:1
	s_nop 1
	v_add_f32_dpp v41, v41, v41 quad_perm:[2,3,0,1] row_mask:0xf bank_mask:0xf bound_ctrl:1
	s_nop 1
	v_add_f32_dpp v41, v41, v41 row_half_mirror row_mask:0xf bank_mask:0xf bound_ctrl:1
	s_nop 1
	v_mov_b32_dpp v43, v41 row_mirror row_mask:0xf bank_mask:0xf bound_ctrl:1
	s_and_saveexec_b64 s[12:13], s[0:1]
	s_cbranch_execz .LBB0_581
	v_add_f32_e32 v41, v41, v43
	v_fmamk_f32 v41, v41, 0x3c800000, v23
	v_rsq_f32_e32 v66, v41
	s_nop 0
	v_pk_mul_f32 v[64:65], v[64:65], v[66:67] op_sel_hi:[1,0]
	v_pk_mul_f32 v[58:59], v[58:59], v[66:67] op_sel_hi:[1,0]
	v_pk_mul_f32 v[64:65], v[8:9], v[64:65]
	v_pk_mul_f32 v[58:59], v[10:11], v[58:59]
	v_cvt_pk_bf16_f32 v64, v64, v65
	v_cvt_pk_bf16_f32 v65, v58, v59
	v_lshlrev_b64 v[58:59], 7, v[60:61]
	v_lshl_add_u64 v[58:59], v[16:17], 0, v[58:59]
	global_store_dwordx2 v[58:59], v[64:65], off

; __device__ __forceinline__ unsigned pk2(float lo, float hi) { const f32x2 v = {lo, hi}; const hwbf16x2 b = __builtin_convertvector(v, hwbf16x2); return __builtin_bit_cast(unsigned, b); }
; __device__ __forceinline__ void dsa_prep(const Args& a, unsigned char* lds, int tid) {
;     ...
;         for (int i = 0; i < 8; ++i) {
;             const int row = t0 + 8 * w + i;
;             const bf16* src = QKVI + (size_t)row * QKVI_LD;
; #pragma unroll
;             for (int j = 0; j < 5; ++j) {
;                 const int hh = j * 4 + grp, col = hh * 64 + 4 * sub;
;                 const u32x2 x = *(const u32x2*)(src + col);
;                 f32x4 v = (f32x4){bflo(x.x), bfhi(x.x), bflo(x.y), bfhi(x.y)};
;                 float ss = (v.x * v.x + v.y * v.y) + (v.z * v.z + v.w * v.w);
;                 ss = row16_sum(ss);
;                 const float rstd = __builtin_amdgcn_rsqf(ss * (1.f / 64.f) + 1e-6f);
;                 if (j < 4) { v = v * rstd * qn * QSCALE; u32x2 o; o.x = pk2(v.x, v.y); o.y = pk2(v.z, v.w); *(u32x2*)(QN + (size_t)row * D + col) = o; }
;                 else { v = v * rstd * kn; u32x2 o; o.x = pk2(v.x, v.y); o.y = pk2(v.z, v.w); *(u32x2*)(KN + (size_t)row * 256 + (col - 1024)) = o; }
.LBB0_583:
	s_or_b64 exec, exec, s[12:13]
	v_readlane_b32 s12, v248, 61
	v_readlane_b32 s13, v248, 62
	v_add_u32_e32 v60, 2, v29
	v_ashrrev_i32_e32 v61, 31, v60
	v_mov_b64_e32 v[62:63], s[12:13]
	v_mad_i64_i32 v[62:63], s[12:13], v60, s22, v[62:63]
	v_lshl_add_u64 v[64:65], v[62:63], 0, v[12:13]
	global_load_dwordx2 v[100:101], v[64:65], off
	global_load_dwordx2 v[102:103], v[64:65], off offset:512
	global_load_dwordx2 v[104:105], v[64:65], off offset:1024
	global_load_dwordx2 v[66:67], v[64:65], off offset:1536
	v_lshlrev_b64 v[72:73], 11, v[60:61]
	v_lshl_add_u64 v[72:73], v[26:27], 0, v[72:73]
	s_waitcnt vmcnt(3)
	v_lshlrev_b32_e32 v75, 16, v101
	v_lshlrev_b32_e32 v74, 16, v100
	v_and_b32_e32 v101, 0xffff0000, v101
	v_and_b32_e32 v100, 0xffff0000, v100
	v_pk_mul_f32 v[76:77], v[100:101], v[100:101]
	v_mov_b32_e32 v78, v75
	v_pk_fma_f32 v[76:77], v[74:75], v[74:75], v[76:77]
	v_mov_b32_e32 v79, v101
	v_add_f32_e32 v41, v76, v77
	v_mov_b32_e32 v75, v100
	s_nop 0
	v_add_f32_dpp v41, v41, v41 quad_perm:[1,0,3,2] row_mask:0xf bank_mask:0xf bound_ctrl:1
	s_nop 1
	v_add_f32_dpp v41, v41, v41 quad_perm:[2,3,0,1] row_mask:0xf bank_mask:0xf bound_ctrl:1
	s_nop 1
	v_add_f32_dpp v41, v41, v41 row_half_mirror row_mask:0xf bank_mask:0xf bound_ctrl:1
	s_nop 1
	v_add_f32_dpp v41, v41, v41 row_mirror row_mask:0xf bank_mask:0xf bound_ctrl:1
	v_fmamk_f32 v41, v41, 0x3c800000, v23
	v_rsq_f32_e32 v76, v41
	s_nop 0
	v_pk_mul_f32 v[100:101], v[76:77], v[78:79] op_sel_hi:[0,1]
	v_pk_mul_f32 v[74:75], v[76:77], v[74:75] op_sel_hi:[0,1]
	v_pk_mul_f32 v[74:75], v[0:1], v[74:75]
	v_pk_mul_f32 v[100:101], v[2:3], v[100:101]
	v_pk_mul_f32 v[74:75], v[74:75], s[8:9] op_sel_hi:[1,0]
	v_pk_mul_f32 v[100:101], v[100:101], s[8:9] op_sel_hi:[1,0]
	v_cvt_pk_bf16_f32 v74, v74, v75
	v_cvt_pk_bf16_f32 v75, v100, v101
	global_store_dwordx2 v[72:73], v[74:75], off
	s_waitcnt vmcnt(3)
	v_lshlrev_b32_e32 v75, 16, v103
	v_lshlrev_b32_e32 v74, 16, v102
	v_and_b32_e32 v103, 0xffff0000, v103
	v_and_b32_e32 v102, 0xffff0000, v102
	v_pk_mul_f32 v[76:77], v[102:103], v[102:103]
	v_mov_b32_e32 v78, v75
	v_pk_fma_f32 v[76:77], v[74:75], v[74:75], v[76:77]
	v_mov_b32_e32 v79, v103
	v_add_f32_e32 v41, v76, v77
	v_mov_b32_e32 v75, v102
	s_nop 0
	v_add_f32_dpp v41, v41, v41 quad_perm:[1,0,3,2] row_mask:0xf bank_mask:0xf bound_ctrl:1
	s_nop 1
	v_add_f32_dpp v41, v41, v41 quad_perm:[2,3,0,1] row_mask:0xf bank_mask:0xf bound_ctrl:1
	s_nop 1
	v_add_f32_dpp v41, v41, v41 row_half_mirror row_mask:0xf bank_mask:0xf bound_ctrl:1
	s_nop 1
	v_add_f32_dpp v41, v41, v41 row_mirror row_mask:0xf bank_mask:0xf bound_ctrl:1
	v_fmamk_f32 v41, v41, 0x3c800000, v23
	v_rsq_f32_e32 v76, v41
	s_nop 0
	v_pk_mul_f32 v[102:103], v[76:77], v[78:79] op_sel_hi:[0,1]
	v_pk_mul_f32 v[74:75], v[76:77], v[74:75] op_sel_hi:[0,1]
	v_pk_mul_f32 v[74:75], v[0:1], v[74:75]
	v_pk_mul_f32 v[102:103], v[2:3], v[102:103]
	v_pk_mul_f32 v[74:75], v[74:75], s[8:9] op_sel_hi:[1,0]
	v_pk_mul_f32 v[102:103], v[102:103], s[8:9] op_sel_hi:[1,0]
	v_cvt_pk_bf16_f32 v74, v74, v75
	v_cvt_pk_bf16_f32 v75, v102, v103
	global_store_dwordx2 v[72:73], v[74:75], off offset:512
	s_waitcnt vmcnt(3)
	v_lshlrev_b32_e32 v75, 16, v105
	v_lshlrev_b32_e32 v74, 16, v104
	v_and_b32_e32 v105, 0xffff0000, v105
	v_and_b32_e32 v104, 0xffff0000, v104
	v_pk_mul_f32 v[76:77], v[104:105], v[104:105]
	v_mov_b32_e32 v78, v75
	v_pk_fma_f32 v[76:77], v[74:75], v[74:75], v[76:77]
	v_mov_b32_e32 v79, v105
	v_add_f32_e32 v41, v76, v77
	v_mov_b32_e32 v75, v104
	s_nop 0
	v_add_f32_dpp v41, v41, v41 quad_perm:[1,0,3,2] row_mask:0xf bank_mask:0xf bound_ctrl:1
	s_nop 1
	v_add_f32_dpp v41, v41, v41 quad_perm:[2,3,0,1] row_mask:0xf bank_mask:0xf bound_ctrl:1
	s_nop 1
	v_add_f32_dpp v41, v41, v41 row_half_mirror row_mask:0xf bank_mask:0xf bound_ctrl:1
	s_nop 1
	v_add_f32_dpp v41, v41, v41 row_mirror row_mask:0xf bank_mask:0xf bound_ctrl:1
	v_fmamk_f32 v41, v41, 0x3c800000, v23
	v_rsq_f32_e32 v76, v41
	s_nop 0
	v_pk_mul_f32 v[104:105], v[76:77], v[78:79] op_sel_hi:[0,1]
	v_pk_mul_f32 v[74:75], v[76:77], v[74:75] op_sel_hi:[0,1]
	v_pk_mul_f32 v[74:75], v[0:1], v[74:75]
	v_pk_mul_f32 v[104:105], v[2:3], v[104:105]
	v_pk_mul_f32 v[74:75], v[74:75], s[8:9] op_sel_hi:[1,0]
	v_pk_mul_f32 v[104:105], v[104:105], s[8:9] op_sel_hi:[1,0]
	v_cvt_pk_bf16_f32 v74, v74, v75
	v_cvt_pk_bf16_f32 v75, v104, v105
	global_store_dwordx2 v[72:73], v[74:75], off offset:1024
	s_waitcnt vmcnt(3)
; __device__ __forceinline__ unsigned pk2(float lo, float hi) { const f32x2 v = {lo, hi}; const hwbf16x2 b = __builtin_convertvector(v, hwbf16x2); return __builtin_bit_cast(unsigned, b); }
; __device__ __forceinline__ void dsa_prep(const Args& a, unsigned char* lds, int tid) {
;     ...
;             for (int j = 0; j < 5; ++j) {
;                 const int hh = j * 4 + grp, col = hh * 64 + 4 * sub;
;                 const u32x2 x = *(const u32x2*)(src + col);
;                 f32x4 v = (f32x4){bflo(x.x), bfhi(x.x), bflo(x.y), bfhi(x.y)};
;                 float ss = (v.x * v.x + v.y * v.y) + (v.z * v.z + v.w * v.w);
;                 ss = row16_sum(ss);
;                 const float rstd = __builtin_amdgcn_rsqf(ss * (1.f / 64.f) + 1e-6f);
;                 if (j < 4) { v = v * rstd * qn * QSCALE; u32x2 o; o.x = pk2(v.x, v.y); o.y = pk2(v.z, v.w); *(u32x2*)(QN + (size_t)row * D + col) = o; }
;                 else { v = v * rstd * kn; u32x2 o; o.x = pk2(v.x, v.y); o.y = pk2(v.z, v.w); *(u32x2*)(KN + (size_t)row * 256 + (col - 1024)) = o; }
;             }
;             {
;                 const u32x2 x = *(const u32x2*)(src + 2048 + 4 * sub);
;                 f32x4 v = (f32x4){bflo(x.x), bfhi(x.x), bflo(x.y), bfhi(x.y)};
;                 float ss = (v.x * v.x + v.y * v.y) + (v.z * v.z + v.w * v.w);
;                 ss = row16_sum(ss);
;                 const float rstd = __builtin_amdgcn_rsqf(ss * (1.f / 64.f) + 1e-6f);
;                 v = v * rstd * ikn;
;                 if (grp == 0) { u32x2 o; o.x = pk2(v.x, v.y); o.y = pk2(v.z, v.w); *(u32x2*)(IKN + (size_t)row * 64 + 4 * sub) = o; }
	v_lshlrev_b32_e32 v75, 16, v67
	v_lshlrev_b32_e32 v74, 16, v66
	v_and_b32_e32 v67, 0xffff0000, v67
	v_and_b32_e32 v66, 0xffff0000, v66
	v_pk_mul_f32 v[76:77], v[66:67], v[66:67]
	v_mov_b32_e32 v78, v75
	v_pk_fma_f32 v[76:77], v[74:75], v[74:75], v[76:77]
	v_mov_b32_e32 v79, v67
	v_add_f32_e32 v41, v76, v77
	v_mov_b32_e32 v75, v66
	s_nop 0
	v_add_f32_dpp v41, v41, v41 quad_perm:[1,0,3,2] row_mask:0xf bank_mask:0xf bound_ctrl:1
	s_nop 1
	v_add_f32_dpp v41, v41, v41 quad_perm:[2,3,0,1] row_mask:0xf bank_mask:0xf bound_ctrl:1
	s_nop 1
	v_add_f32_dpp v41, v41, v41 row_half_mirror row_mask:0xf bank_mask:0xf bound_ctrl:1
	s_nop 1
	v_add_f32_dpp v41, v41, v41 row_mirror row_mask:0xf bank_mask:0xf bound_ctrl:1
	v_fmamk_f32 v41, v41, 0x3c800000, v23
	v_rsq_f32_e32 v76, v41
	v_mov_b32_e32 v41, v13
	v_pk_mul_f32 v[66:67], v[76:77], v[78:79] op_sel_hi:[0,1]
	v_pk_mul_f32 v[74:75], v[76:77], v[74:75] op_sel_hi:[0,1]
	v_pk_mul_f32 v[74:75], v[0:1], v[74:75]
	v_pk_mul_f32 v[66:67], v[2:3], v[66:67]
	v_pk_mul_f32 v[74:75], v[74:75], s[8:9] op_sel_hi:[1,0]
	v_pk_mul_f32 v[66:67], v[66:67], s[8:9] op_sel_hi:[1,0]
	v_cvt_pk_bf16_f32 v74, v74, v75
	v_cvt_pk_bf16_f32 v75, v66, v67
	global_store_dwordx2 v[72:73], v[74:75], off offset:1536
	global_load_dwordx2 v[64:65], v[64:65], off offset:2048
	v_lshl_add_u64 v[72:73], v[62:63], 0, v[40:41]
	v_lshlrev_b64 v[66:67], 9, v[60:61]
	v_add_co_u32_e32 v72, vcc, s9, v72
	v_lshl_add_u64 v[66:67], v[24:25], 0, v[66:67]
	s_nop 0
	v_addc_co_u32_e32 v73, vcc, 0, v73, vcc
	v_add_co_u32_e32 v66, vcc, s21, v66
	s_waitcnt vmcnt(0)
	v_lshlrev_b32_e32 v75, 16, v65
	v_lshlrev_b32_e32 v74, 16, v64
	v_and_b32_e32 v65, 0xffff0000, v65
	v_and_b32_e32 v64, 0xffff0000, v64
	v_pk_mul_f32 v[76:77], v[64:65], v[64:65]
	v_mov_b32_e32 v78, v74
	v_pk_fma_f32 v[76:77], v[74:75], v[74:75], v[76:77]
	v_mov_b32_e32 v79, v64
	v_add_f32_e32 v41, v76, v77
	v_mov_b32_e32 v64, v75
	v_addc_co_u32_e32 v67, vcc, 0, v67, vcc
	v_add_f32_dpp v41, v41, v41 quad_perm:[1,0,3,2] row_mask:0xf bank_mask:0xf bound_ctrl:1
	s_nop 1
	v_add_f32_dpp v41, v41, v41 quad_perm:[2,3,0,1] row_mask:0xf bank_mask:0xf bound_ctrl:1
	s_nop 1
	v_add_f32_dpp v41, v41, v41 row_half_mirror row_mask:0xf bank_mask:0xf bound_ctrl:1
	s_nop 1
	v_add_f32_dpp v41, v41, v41 row_mirror row_mask:0xf bank_mask:0xf bound_ctrl:1
	v_fmamk_f32 v41, v41, 0x3c800000, v23
	v_rsq_f32_e32 v76, v41
	s_nop 0
	v_pk_mul_f32 v[74:75], v[76:77], v[78:79] op_sel_hi:[0,1]
	v_pk_mul_f32 v[64:65], v[76:77], v[64:65] op_sel_hi:[0,1]
	v_pk_mul_f32 v[64:65], v[6:7], v[64:65]
	v_pk_mul_f32 v[74:75], v[4:5], v[74:75]
	s_nop 0
	v_cvt_pk_bf16_f32 v74, v74, v75
	v_cvt_pk_bf16_f32 v75, v64, v65
	global_store_dwordx2 v[66:67], v[74:75], off
	global_load_dwordx2 v[64:65], v[72:73], off
	s_waitcnt vmcnt(0)
	v_lshlrev_b32_e32 v66, 16, v64
	v_and_b32_e32 v67, 0xffff0000, v64
	v_lshlrev_b32_e32 v64, 16, v65
	v_and_b32_e32 v65, 0xffff0000, v65
	v_mul_f32_e32 v41, v67, v67
	v_mul_f32_e32 v43, v65, v65
	v_fmac_f32_e32 v41, v66, v66
	v_fmac_f32_e32 v43, v64, v64
	v_add_f32_e32 v41, v41, v43
	s_nop 1
	v_add_f32_dpp v41, v41, v41 quad_perm:[1,0,3,2] row_mask:0xf bank_mask:0xf bound_ctrl:1
	s_nop 1
	v_add_f32_dpp v41, v41, v41 quad_perm:[2,3,0,1] row_mask:0xf bank_mask:0xf bound_ctrl:1
	s_nop 1
	v_add_f32_dpp v41, v41, v41 row_half_mirror row_mask:0xf bank_mask:0xf bound_ctrl:1
	s_nop 1
	v_mov_b32_dpp v43, v41 row_mirror row_mask:0xf bank_mask:0xf bound_ctrl:1
	s_and_saveexec_b64 s[12:13], s[0:1]
	s_cbranch_execz .LBB0_585
	v_add_f32_e32 v41, v41, v43
	v_fmamk_f32 v41, v41, 0x3c800000, v23
	v_rsq_f32_e32 v72, v41
	s_nop 0
	v_pk_mul_f32 v[66:67], v[66:67], v[72:73] op_sel_hi:[1,0]
	v_pk_mul_f32 v[64:65], v[64:65], v[72:73] op_sel_hi:[1,0]
	v_pk_mul_f32 v[66:67], v[8:9], v[66:67]
	v_pk_mul_f32 v[64:65], v[10:11], v[64:65]
	v_cvt_pk_bf16_f32 v66, v66, v67
	v_cvt_pk_bf16_f32 v67, v64, v65
	v_lshlrev_b64 v[64:65], 7, v[60:61]
	v_lshl_add_u64 v[64:65], v[16:17], 0, v[64:65]
	global_store_dwordx2 v[64:65], v[66:67], off

; __device__ __forceinline__ unsigned pk2(float lo, float hi) { const f32x2 v = {lo, hi}; const hwbf16x2 b = __builtin_convertvector(v, hwbf16x2); return __builtin_bit_cast(unsigned, b); }
; __device__ __forceinline__ void dsa_prep(const Args& a, unsigned char* lds, int tid) {
;     ...
;         for (int i = 0; i < 8; ++i) {
;             const int row = t0 + 8 * w + i;
;             const bf16* src = QKVI + (size_t)row * QKVI_LD;
; #pragma unroll
;             for (int j = 0; j < 5; ++j) {
;                 const int hh = j * 4 + grp, col = hh * 64 + 4 * sub;
;                 const u32x2 x = *(const u32x2*)(src + col);
;                 f32x4 v = (f32x4){bflo(x.x), bfhi(x.x), bflo(x.y), bfhi(x.y)};
;                 float ss = (v.x * v.x + v.y * v.y) + (v.z * v.z + v.w * v.w);
;                 ss = row16_sum(ss);
;                 const float rstd = __builtin_amdgcn_rsqf(ss * (1.f / 64.f) + 1e-6f);
;                 if (j < 4) { v = v * rstd * qn * QSCALE; u32x2 o; o.x = pk2(v.x, v.y); o.y = pk2(v.z, v.w); *(u32x2*)(QN + (size_t)row * D + col) = o; }
;                 else { v = v * rstd * kn; u32x2 o; o.x = pk2(v.x, v.y); o.y = pk2(v.z, v.w); *(u32x2*)(KN + (size_t)row * 256 + (col - 1024)) = o; }
.LBB0_587:
	s_or_b64 exec, exec, s[12:13]
	v_readlane_b32 s12, v248, 61
	v_readlane_b32 s13, v248, 62
	v_add_u32_e32 v60, 3, v29
	v_ashrrev_i32_e32 v61, 31, v60
	v_mov_b64_e32 v[62:63], s[12:13]
	v_mad_i64_i32 v[62:63], s[12:13], v60, s22, v[62:63]
	v_lshl_add_u64 v[64:65], v[62:63], 0, v[12:13]
	global_load_dwordx2 v[100:101], v[64:65], off
	global_load_dwordx2 v[102:103], v[64:65], off offset:512
	global_load_dwordx2 v[104:105], v[64:65], off offset:1024
	global_load_dwordx2 v[66:67], v[64:65], off offset:1536
	v_lshlrev_b64 v[72:73], 11, v[60:61]
	v_lshl_add_u64 v[72:73], v[26:27], 0, v[72:73]
	v_mov_b32_e32 v41, v13
	s_waitcnt vmcnt(3)
	v_lshlrev_b32_e32 v75, 16, v101
	v_lshlrev_b32_e32 v74, 16, v100
	v_and_b32_e32 v101, 0xffff0000, v101
	v_and_b32_e32 v100, 0xffff0000, v100
	v_pk_mul_f32 v[76:77], v[100:101], v[100:101]
	v_mov_b32_e32 v78, v75
	v_pk_fma_f32 v[76:77], v[74:75], v[74:75], v[76:77]
	v_mov_b32_e32 v79, v101
	v_add_f32_e32 v29, v76, v77
	v_mov_b32_e32 v75, v100
	s_nop 0
	v_add_f32_dpp v29, v29, v29 quad_perm:[1,0,3,2] row_mask:0xf bank_mask:0xf bound_ctrl:1
	s_nop 1
	v_add_f32_dpp v29, v29, v29 quad_perm:[2,3,0,1] row_mask:0xf bank_mask:0xf bound_ctrl:1
	s_nop 1
	v_add_f32_dpp v29, v29, v29 row_half_mirror row_mask:0xf bank_mask:0xf bound_ctrl:1
	s_nop 1
	v_add_f32_dpp v29, v29, v29 row_mirror row_mask:0xf bank_mask:0xf bound_ctrl:1
	v_fmamk_f32 v29, v29, 0x3c800000, v23
	v_rsq_f32_e32 v76, v29
	s_nop 0
	v_pk_mul_f32 v[100:101], v[76:77], v[78:79] op_sel_hi:[0,1]
	v_pk_mul_f32 v[74:75], v[76:77], v[74:75] op_sel_hi:[0,1]
	v_pk_mul_f32 v[74:75], v[0:1], v[74:75]
	v_pk_mul_f32 v[100:101], v[2:3], v[100:101]
	v_pk_mul_f32 v[74:75], v[74:75], s[8:9] op_sel_hi:[1,0]
	v_pk_mul_f32 v[100:101], v[100:101], s[8:9] op_sel_hi:[1,0]
	v_cvt_pk_bf16_f32 v74, v74, v75
	v_cvt_pk_bf16_f32 v75, v100, v101
	global_store_dwordx2 v[72:73], v[74:75], off
	s_waitcnt vmcnt(3)
	v_lshlrev_b32_e32 v75, 16, v103
	v_lshlrev_b32_e32 v74, 16, v102
	v_and_b32_e32 v103, 0xffff0000, v103
	v_and_b32_e32 v102, 0xffff0000, v102
	v_pk_mul_f32 v[76:77], v[102:103], v[102:103]
	v_mov_b32_e32 v78, v75
	v_pk_fma_f32 v[76:77], v[74:75], v[74:75], v[76:77]
	v_mov_b32_e32 v79, v103
	v_add_f32_e32 v29, v76, v77
	v_mov_b32_e32 v75, v102
	s_nop 0
	v_add_f32_dpp v29, v29, v29 quad_perm:[1,0,3,2] row_mask:0xf bank_mask:0xf bound_ctrl:1
	s_nop 1
	v_add_f32_dpp v29, v29, v29 quad_perm:[2,3,0,1] row_mask:0xf bank_mask:0xf bound_ctrl:1
	s_nop 1
	v_add_f32_dpp v29, v29, v29 row_half_mirror row_mask:0xf bank_mask:0xf bound_ctrl:1
	s_nop 1
	v_add_f32_dpp v29, v29, v29 row_mirror row_mask:0xf bank_mask:0xf bound_ctrl:1
	v_fmamk_f32 v29, v29, 0x3c800000, v23
	v_rsq_f32_e32 v76, v29
	s_nop 0
	v_pk_mul_f32 v[102:103], v[76:77], v[78:79] op_sel_hi:[0,1]
	v_pk_mul_f32 v[74:75], v[76:77], v[74:75] op_sel_hi:[0,1]
	v_pk_mul_f32 v[74:75], v[0:1], v[74:75]
	v_pk_mul_f32 v[102:103], v[2:3], v[102:103]
	v_pk_mul_f32 v[74:75], v[74:75], s[8:9] op_sel_hi:[1,0]
	v_pk_mul_f32 v[102:103], v[102:103], s[8:9] op_sel_hi:[1,0]
	v_cvt_pk_bf16_f32 v74, v74, v75
	v_cvt_pk_bf16_f32 v75, v102, v103
	global_store_dwordx2 v[72:73], v[74:75], off offset:512
	s_waitcnt vmcnt(3)
	v_lshlrev_b32_e32 v75, 16, v105
	v_lshlrev_b32_e32 v74, 16, v104
	v_and_b32_e32 v105, 0xffff0000, v105
	v_and_b32_e32 v104, 0xffff0000, v104
	v_pk_mul_f32 v[76:77], v[104:105], v[104:105]
	v_mov_b32_e32 v78, v75
	v_pk_fma_f32 v[76:77], v[74:75], v[74:75], v[76:77]
	v_mov_b32_e32 v79, v105
	v_add_f32_e32 v29, v76, v77
	v_mov_b32_e32 v75, v104
	s_nop 0
	v_add_f32_dpp v29, v29, v29 quad_perm:[1,0,3,2] row_mask:0xf bank_mask:0xf bound_ctrl:1
	s_nop 1
	v_add_f32_dpp v29, v29, v29 quad_perm:[2,3,0,1] row_mask:0xf bank_mask:0xf bound_ctrl:1
	s_nop 1
	v_add_f32_dpp v29, v29, v29 row_half_mirror row_mask:0xf bank_mask:0xf bound_ctrl:1
	s_nop 1
	v_add_f32_dpp v29, v29, v29 row_mirror row_mask:0xf bank_mask:0xf bound_ctrl:1
	v_fmamk_f32 v29, v29, 0x3c800000, v23
	v_rsq_f32_e32 v76, v29
	s_nop 0
	v_pk_mul_f32 v[104:105], v[76:77], v[78:79] op_sel_hi:[0,1]
	v_pk_mul_f32 v[74:75], v[76:77], v[74:75] op_sel_hi:[0,1]
	v_pk_mul_f32 v[74:75], v[0:1], v[74:75]
	v_pk_mul_f32 v[104:105], v[2:3], v[104:105]
	v_pk_mul_f32 v[74:75], v[74:75], s[8:9] op_sel_hi:[1,0]
	v_pk_mul_f32 v[104:105], v[104:105], s[8:9] op_sel_hi:[1,0]
	v_cvt_pk_bf16_f32 v74, v74, v75
	v_cvt_pk_bf16_f32 v75, v104, v105
	global_store_dwordx2 v[72:73], v[74:75], off offset:1024
	s_waitcnt vmcnt(3)
; __device__ __forceinline__ unsigned pk2(float lo, float hi) { const f32x2 v = {lo, hi}; const hwbf16x2 b = __builtin_convertvector(v, hwbf16x2); return __builtin_bit_cast(unsigned, b); }
; __device__ __forceinline__ void dsa_prep(const Args& a, unsigned char* lds, int tid) {
;     ...
;             for (int j = 0; j < 5; ++j) {
;                 const int hh = j * 4 + grp, col = hh * 64 + 4 * sub;
;                 const u32x2 x = *(const u32x2*)(src + col);
;                 f32x4 v = (f32x4){bflo(x.x), bfhi(x.x), bflo(x.y), bfhi(x.y)};
;                 float ss = (v.x * v.x + v.y * v.y) + (v.z * v.z + v.w * v.w);
;                 ss = row16_sum(ss);
;                 const float rstd = __builtin_amdgcn_rsqf(ss * (1.f / 64.f) + 1e-6f);
;                 if (j < 4) { v = v * rstd * qn * QSCALE; u32x2 o; o.x = pk2(v.x, v.y); o.y = pk2(v.z, v.w); *(u32x2*)(QN + (size_t)row * D + col) = o; }
;                 else { v = v * rstd * kn; u32x2 o; o.x = pk2(v.x, v.y); o.y = pk2(v.z, v.w); *(u32x2*)(KN + (size_t)row * 256 + (col - 1024)) = o; }
;             }
;             {
;                 const u32x2 x = *(const u32x2*)(src + 2048 + 4 * sub);
;                 f32x4 v = (f32x4){bflo(x.x), bfhi(x.x), bflo(x.y), bfhi(x.y)};
;                 float ss = (v.x * v.x + v.y * v.y) + (v.z * v.z + v.w * v.w);
;                 ss = row16_sum(ss);
;                 const float rstd = __builtin_amdgcn_rsqf(ss * (1.f / 64.f) + 1e-6f);
;                 v = v * rstd * ikn;
;                 if (grp == 0) { u32x2 o; o.x = pk2(v.x, v.y); o.y = pk2(v.z, v.w); *(u32x2*)(IKN + (size_t)row * 64 + 4 * sub) = o; }
	v_lshlrev_b32_e32 v75, 16, v67
	v_lshlrev_b32_e32 v74, 16, v66
	v_and_b32_e32 v67, 0xffff0000, v67
	v_and_b32_e32 v66, 0xffff0000, v66
	v_pk_mul_f32 v[76:77], v[66:67], v[66:67]
	v_mov_b32_e32 v78, v75
	v_pk_fma_f32 v[76:77], v[74:75], v[74:75], v[76:77]
	v_mov_b32_e32 v79, v67
	v_add_f32_e32 v29, v76, v77
	v_mov_b32_e32 v75, v66
	s_nop 0
	v_add_f32_dpp v29, v29, v29 quad_perm:[1,0,3,2] row_mask:0xf bank_mask:0xf bound_ctrl:1
	s_nop 1
	v_add_f32_dpp v29, v29, v29 quad_perm:[2,3,0,1] row_mask:0xf bank_mask:0xf bound_ctrl:1
	s_nop 1
	v_add_f32_dpp v29, v29, v29 row_half_mirror row_mask:0xf bank_mask:0xf bound_ctrl:1
	s_nop 1
	v_add_f32_dpp v29, v29, v29 row_mirror row_mask:0xf bank_mask:0xf bound_ctrl:1
	v_fmamk_f32 v29, v29, 0x3c800000, v23
	v_rsq_f32_e32 v76, v29
	s_nop 0
	v_pk_mul_f32 v[66:67], v[76:77], v[78:79] op_sel_hi:[0,1]
	v_pk_mul_f32 v[74:75], v[76:77], v[74:75] op_sel_hi:[0,1]
	v_pk_mul_f32 v[74:75], v[0:1], v[74:75]
	v_pk_mul_f32 v[66:67], v[2:3], v[66:67]
	v_pk_mul_f32 v[74:75], v[74:75], s[8:9] op_sel_hi:[1,0]
	v_pk_mul_f32 v[66:67], v[66:67], s[8:9] op_sel_hi:[1,0]
	v_cvt_pk_bf16_f32 v74, v74, v75
	v_cvt_pk_bf16_f32 v75, v66, v67
	global_store_dwordx2 v[72:73], v[74:75], off offset:1536
	global_load_dwordx2 v[64:65], v[64:65], off offset:2048
	v_lshl_add_u64 v[72:73], v[62:63], 0, v[40:41]
	v_lshlrev_b64 v[66:67], 9, v[60:61]
	v_add_co_u32_e32 v72, vcc, s9, v72
	v_lshl_add_u64 v[66:67], v[24:25], 0, v[66:67]
	s_nop 0
	v_addc_co_u32_e32 v73, vcc, 0, v73, vcc
	v_add_co_u32_e32 v66, vcc, s21, v66
	s_waitcnt vmcnt(0)
	v_lshlrev_b32_e32 v75, 16, v65
	v_lshlrev_b32_e32 v74, 16, v64
	v_and_b32_e32 v65, 0xffff0000, v65
	v_and_b32_e32 v64, 0xffff0000, v64
	v_pk_mul_f32 v[76:77], v[64:65], v[64:65]
	v_mov_b32_e32 v78, v74
	v_pk_fma_f32 v[76:77], v[74:75], v[74:75], v[76:77]
	v_mov_b32_e32 v79, v64
	v_add_f32_e32 v29, v76, v77
	v_mov_b32_e32 v64, v75
	v_addc_co_u32_e32 v67, vcc, 0, v67, vcc
	v_add_f32_dpp v29, v29, v29 quad_perm:[1,0,3,2] row_mask:0xf bank_mask:0xf bound_ctrl:1
	s_nop 1
	v_add_f32_dpp v29, v29, v29 quad_perm:[2,3,0,1] row_mask:0xf bank_mask:0xf bound_ctrl:1
	s_nop 1
	v_add_f32_dpp v29, v29, v29 row_half_mirror row_mask:0xf bank_mask:0xf bound_ctrl:1
	s_nop 1
	v_add_f32_dpp v29, v29, v29 row_mirror row_mask:0xf bank_mask:0xf bound_ctrl:1
	v_fmamk_f32 v29, v29, 0x3c800000, v23
	v_rsq_f32_e32 v76, v29
	s_nop 0
	v_pk_mul_f32 v[74:75], v[76:77], v[78:79] op_sel_hi:[0,1]
	v_pk_mul_f32 v[64:65], v[76:77], v[64:65] op_sel_hi:[0,1]
	v_pk_mul_f32 v[64:65], v[6:7], v[64:65]
	v_pk_mul_f32 v[74:75], v[4:5], v[74:75]
	s_nop 0
	v_cvt_pk_bf16_f32 v74, v74, v75
	v_cvt_pk_bf16_f32 v75, v64, v65
	global_store_dwordx2 v[66:67], v[74:75], off
	global_load_dwordx2 v[64:65], v[72:73], off
	s_waitcnt vmcnt(0)
	v_lshlrev_b32_e32 v66, 16, v64
	v_and_b32_e32 v67, 0xffff0000, v64
	v_lshlrev_b32_e32 v64, 16, v65
	v_and_b32_e32 v65, 0xffff0000, v65
	v_mul_f32_e32 v29, v67, v67
	v_mul_f32_e32 v41, v65, v65
	v_fmac_f32_e32 v29, v66, v66
	v_fmac_f32_e32 v41, v64, v64
	v_add_f32_e32 v29, v29, v41
	s_nop 1
	v_add_f32_dpp v29, v29, v29 quad_perm:[1,0,3,2] row_mask:0xf bank_mask:0xf bound_ctrl:1
	s_nop 1
	v_add_f32_dpp v29, v29, v29 quad_perm:[2,3,0,1] row_mask:0xf bank_mask:0xf bound_ctrl:1
	s_nop 1
	v_add_f32_dpp v29, v29, v29 row_half_mirror row_mask:0xf bank_mask:0xf bound_ctrl:1
	s_nop 1
	v_mov_b32_dpp v41, v29 row_mirror row_mask:0xf bank_mask:0xf bound_ctrl:1
	s_and_saveexec_b64 s[12:13], s[0:1]
	s_cbranch_execz .LBB0_589
	v_add_f32_e32 v29, v29, v41
	v_fmamk_f32 v29, v29, 0x3c800000, v23
	v_rsq_f32_e32 v72, v29
	s_nop 0
	v_pk_mul_f32 v[66:67], v[66:67], v[72:73] op_sel_hi:[1,0]
	v_pk_mul_f32 v[64:65], v[64:65], v[72:73] op_sel_hi:[1,0]
	v_pk_mul_f32 v[66:67], v[8:9], v[66:67]
	v_pk_mul_f32 v[64:65], v[10:11], v[64:65]
	v_cvt_pk_bf16_f32 v66, v66, v67
	v_cvt_pk_bf16_f32 v67, v64, v65
	v_lshlrev_b64 v[64:65], 7, v[60:61]
	v_lshl_add_u64 v[64:65], v[16:17], 0, v[64:65]
	global_store_dwordx2 v[64:65], v[66:67], off
